# delta-rule scan phase: static s_setprio 1 for waves 4-7 (on top of the attention static priority)
# baseline (speedup 1.0000x reference)
; __device__ __forceinline__ int bidx() { int b = blockIdx.x; OPAQUE_S(b); return b; }
; __device__ __forceinline__ void gdn_phase(const Args& a, LAS unsigned char* lds, int slot) {
;     ...
; #pragma unroll 1
;     for (int item = bidx(); item < 256 + 128; item += gridDim.x) {
;         const bool samp = item >= 256;
;         const int it = samp ? item - 256 : item, b = it >> 3, h = it & 7;
;         const int nch = samp ? 1 : 32, R = samp ? 32 : 64;
;         const size_t row0 = samp ? (size_t)NTP + b * 32 : (size_t)b * 2048;
;         const float* hist = a.in[4] + (size_t)(slot * 16 + b) * 3 * 3072;
;         const int ci0 = samp ? 8192 + b * 8 + h : (b * 32) * 8 + h;
.LBB0_2374:
	s_or_b64 exec, exec, s[0:1]
	v_mov_b32_e32 v144, v187
	s_mov_b32 s22, s69
	s_waitcnt lgkmcnt(0)
	s_barrier
	v_readfirstlane_b32 s0, v187
	s_cmp_lt_u32 s0, 0x100
	s_cbranch_scc1 .Lprio_gdn_lo
	s_setprio 1
.Lprio_gdn_lo:
	s_cmpk_gt_i32 s22, 0x17f
	s_cbranch_scc1 .LBB0_2478
	v_readlane_b32 s0, v253, 50
	v_readlane_b32 s4, v251, 38
	v_readlane_b32 s1, v253, 51
	v_readlane_b32 s20, v254, 61
	v_readlane_b32 s5, v251, 39
	v_readlane_b32 s6, v251, 40
	v_readlane_b32 s7, v251, 41
	v_readlane_b32 s8, v251, 42
	v_readlane_b32 s9, v251, 43
	s_mov_b32 s3, s1
	s_lshl_b32 s2, s20, 7
	v_writelane_b32 v253, s0, 50
	v_readlane_b32 s10, v251, 44
	v_readlane_b32 s11, v251, 45
	v_readlane_b32 s12, v251, 46
	v_readlane_b32 s13, v251, 47
	s_mov_b64 s[4:5], s[8:9]
	v_writelane_b32 v253, s1, 51
	s_lshl_b64 s[0:1], s[2:3], 2
	s_mov_b64 s[6:7], s[10:11]
	s_mov_b64 s[8:9], s[12:13]
	s_add_u32 s2, s8, s0
	s_addc_u32 s3, s9, s1
	s_lshl_b32 s23, s20, 4
	s_lshl_b32 s24, s20, 5
	v_readlane_b32 s21, v254, 62
	v_readlane_b32 s14, v251, 48
	v_readlane_b32 s15, v251, 49
	v_readlane_b32 s16, v251, 50
	v_readlane_b32 s17, v251, 51
	v_readlane_b32 s18, v251, 52
	v_readlane_b32 s19, v251, 53
	s_branch .LBB0_2377

; __device__ __forceinline__ void xcd_barrier(const XcdBarrier& b) {
;     asm volatile("s_waitcnt vmcnt(0)" ::: "memory");
;     __syncthreads();
;     if (threadIdx.x == 0) {
;         unsigned* bar = b.bar;
;         __builtin_amdgcn_s_waitcnt(0);
;         unsigned nloc = b.st[0], nx = b.st[1];
;         if (nloc == 0u) { xcd_barrier_complete(bar, b.x, nloc, nx); b.st[0] = nloc; b.st[1] = nx; }
.LBB0_2478:
	s_waitcnt vmcnt(0)
	s_setprio 0
	s_barrier
	s_mov_b64 s[0:1], exec
	v_readlane_b32 s2, v251, 4
	v_readlane_b32 s3, v251, 5
	s_and_b64 s[2:3], s[0:1], s[2:3]
	s_mov_b64 exec, s[2:3]
	s_cbranch_execz .LBB0_2530
	v_readlane_b32 s2, v254, 20
	s_waitcnt vmcnt(0) expcnt(0) lgkmcnt(0)
	s_nop 0
	v_mov_b32_e32 v0, s2
	ds_read_b32 v3, v0
	v_readlane_b32 s2, v254, 21
	s_waitcnt lgkmcnt(0)
	v_cmp_ne_u32_e32 vcc, 0, v3
	v_mov_b32_e32 v0, s2
	ds_read_b32 v2, v0
	s_cbranch_vccnz .LBB0_2494
	s_mov_b32 s8, 1
	s_branch .LBB0_2482
